# v_d1 + s_setprio 1/0 around each attention P.V MFMA block (all waves)
# speedup vs baseline: 1.0011x; 1.0011x over previous
.LBB0_1004:
	v_exp_f32_e32 v88, v88
	v_exp_f32_e32 v89, v89
	v_exp_f32_e32 v90, v90
	v_exp_f32_e32 v91, v91
	v_exp_f32_e32 v92, v92
	v_exp_f32_e32 v93, v93
	v_exp_f32_e32 v94, v94
	v_exp_f32_e32 v95, v95
	v_cvt_pk_bf16_f32 v88, v88, v89
	v_cvt_pk_bf16_f32 v89, v90, v91
	v_cvt_pk_bf16_f32 v90, v92, v93
	v_cvt_pk_bf16_f32 v91, v94, v95
	s_add_i32 s6, s87, 0x8000
	s_cmp_lg_u32 s6, 0x18000
	s_cselect_b32 s87, s6, 0
	s_add_i32 s6, s86, 0x8000
	s_setprio 1
	s_waitcnt lgkmcnt(6)
	v_mfma_f32_32x32x16_bf16 v[48:63], v[88:91], v[100:103], v[48:63]
	s_cmp_lg_u32 s6, 0x18000
	s_cselect_b32 s86, s6, 0
	s_add_u32 s48, s48, 0x58000
	s_addc_u32 s49, s49, 0
	s_add_u32 s42, s42, 0x58000
	s_addc_u32 s43, s43, 0
	s_add_u32 s40, s40, 0x58000
	s_waitcnt lgkmcnt(4)
	v_mfma_f32_32x32x16_bf16 v[32:47], v[88:91], v[96:99], v[32:47]
	s_addc_u32 s41, s41, 0
	s_cmp_eq_u32 s84, s85
	s_waitcnt lgkmcnt(2)
	v_mfma_f32_32x32x16_bf16 v[16:31], v[88:91], v[84:87], v[16:31]
	s_waitcnt lgkmcnt(0)
	v_mfma_f32_32x32x16_bf16 v[0:15], v[88:91], v[80:83], v[0:15]
	v_mfma_f32_32x32x16_bf16 v[64:79], v[88:91], v[128:131], v[64:79]
	s_setprio 0
	s_cbranch_scc1 .LBB0_1017

.Latt_dma0:
	ds_read_b64_tr_b16 v[152:153], v156 offset:17408
	ds_read_b64_tr_b16 v[154:155], v156 offset:17920
	ds_read_b64_tr_b16 v[148:149], v156 offset:21504
	ds_read_b64_tr_b16 v[150:151], v156 offset:22016
	ds_read_b64_tr_b16 v[100:101], v156 offset:25600
	ds_read_b64_tr_b16 v[102:103], v156 offset:26112
	ds_read_b64_tr_b16 v[96:97], v156 offset:29696
	ds_read_b64_tr_b16 v[98:99], v156 offset:30208
	s_setprio 1
	s_waitcnt lgkmcnt(14)
	v_mfma_f32_32x32x16_bf16 v[48:63], v[216:219], v[144:147], v[48:63]
	s_andn2_b64 vcc, exec, s[50:51]
	s_waitcnt lgkmcnt(12)
	v_mfma_f32_32x32x16_bf16 v[32:47], v[216:219], v[140:143], v[32:47]
	s_waitcnt lgkmcnt(10)
	v_mfma_f32_32x32x16_bf16 v[16:31], v[216:219], v[136:139], v[16:31]
	s_waitcnt lgkmcnt(8)
	v_mfma_f32_32x32x16_bf16 v[0:15], v[216:219], v[132:135], v[0:15]
	v_cndmask_b32_e64 v132, 0, 1, s[50:51]
	v_cmp_ne_u32_e64 s[6:7], 1, v132
	v_mfma_f32_32x32x16_bf16 v[64:79], v[216:219], v[128:131], v[64:79]
	s_setprio 0

.Latt_dma1:
	ds_read_b64_tr_b16 v[136:137], v156 offset:18432
	ds_read_b64_tr_b16 v[138:139], v156 offset:18944
	ds_read_b64_tr_b16 v[132:133], v156 offset:22528
	ds_read_b64_tr_b16 v[134:135], v156 offset:23040
	ds_read_b64_tr_b16 v[108:109], v156 offset:26624
	ds_read_b64_tr_b16 v[110:111], v156 offset:27136
	ds_read_b64_tr_b16 v[104:105], v156 offset:30720
	ds_read_b64_tr_b16 v[106:107], v156 offset:31232
	s_setprio 1
	s_waitcnt lgkmcnt(14)
	v_mfma_f32_32x32x16_bf16 v[48:63], v[140:143], v[152:155], v[48:63]
	s_and_b64 vcc, exec, s[6:7]
	s_waitcnt lgkmcnt(12)
	v_mfma_f32_32x32x16_bf16 v[32:47], v[140:143], v[148:151], v[32:47]
	s_waitcnt lgkmcnt(10)
	v_mfma_f32_32x32x16_bf16 v[16:31], v[140:143], v[100:103], v[16:31]
	s_waitcnt lgkmcnt(8)
	v_mfma_f32_32x32x16_bf16 v[0:15], v[140:143], v[96:99], v[0:15]
	v_mfma_f32_32x32x16_bf16 v[64:79], v[140:143], v[128:131], v[64:79]
	s_setprio 0

.Latt_dma2:
	ds_read_b64_tr_b16 v[100:101], v156 offset:19456
	ds_read_b64_tr_b16 v[102:103], v156 offset:19968
	ds_read_b64_tr_b16 v[96:97], v156 offset:23552
	ds_read_b64_tr_b16 v[98:99], v156 offset:24064
	ds_read_b64_tr_b16 v[84:85], v156 offset:27648
	ds_read_b64_tr_b16 v[86:87], v156 offset:28160
	ds_read_b64_tr_b16 v[80:81], v156 offset:31744
	ds_read_b64_tr_b16 v[82:83], v156 offset:32256
	s_setprio 1
	s_waitcnt lgkmcnt(14)
	v_mfma_f32_32x32x16_bf16 v[48:63], v[140:143], v[136:139], v[48:63]
	s_and_b64 vcc, exec, s[6:7]
	s_waitcnt lgkmcnt(12)
	v_mfma_f32_32x32x16_bf16 v[32:47], v[140:143], v[132:135], v[32:47]
	s_waitcnt lgkmcnt(10)
	v_mfma_f32_32x32x16_bf16 v[16:31], v[140:143], v[108:111], v[16:31]
	s_waitcnt lgkmcnt(8)
	v_mfma_f32_32x32x16_bf16 v[0:15], v[140:143], v[104:107], v[0:15]
	v_mfma_f32_32x32x16_bf16 v[64:79], v[140:143], v[128:131], v[64:79]
	s_setprio 0
	s_cbranch_vccnz .LBB0_1004
	s_add_u32 s6, s42, 0x480
	s_addc_u32 s7, s43, 0
	s_add_i32 s50, s86, s68
	s_addk_i32 s50, 0x2000
	s_mov_b32 s51, m0
	s_mov_b32 m0, s50
	s_nop 0
	global_load_lds_dwordx4 v212, s[6:7]
	s_mov_b32 m0, s51
	s_branch .LBB0_1004
